# conversion of next layer's W_up/W_down split 2:1 between idle WG groups of down-proj phase; one wave per WG polls the deferred-tile counter (earlier, t=36) instead of all waves
# speedup vs baseline: 1.0282x; 1.0282x over previous
.LBB0_409:
	v_readlane_b32 s2, v255, 60
	s_cmp_eq_u32 s2, 0
	s_cbranch_scc1 .Ldefer_conv_orig
	v_readlane_b32 s2, v255, 58
	s_cmp_eq_u32 s2, 1
	s_cbranch_scc0 .LBB0_440
	s_cmpk_lt_i32 s70, 0xe0
	s_cbranch_scc0 .Ldefer_c224
	s_waitcnt vmcnt(0) lgkmcnt(0)
	s_barrier
	v_cmp_eq_u32_e32 vcc, 0, v225
	s_and_saveexec_b64 s[2:3], vcc
	s_cbranch_execz .Ldefer_sig_end
	buffer_wbl2 sc1
	s_waitcnt vmcnt(0)
	s_load_dwordx2 s[6:7], s[0:1], 0xb0
	s_lshl_b32 s4, s18, 6
	s_add_i32 s4, s4, 0x3800
	s_waitcnt lgkmcnt(0)
	s_add_u32 s6, s6, s4
	s_addc_u32 s7, s7, 0
	v_mov_b32_e32 v0, 1
	global_atomic_add v1, v0, s[6:7]
	s_waitcnt vmcnt(0)
.Ldefer_sig_end:
	s_or_b64 exec, exec, s[2:3]
	s_mov_b32 s2, 0xfffffc00
	s_branch .Ldefer_cset
.Ldefer_c224:
	s_mov_b32 s2, 0xfffff900
.Ldefer_cset:
	v_writelane_b32 v255, s2, 61
	s_cmp_gt_i32 s82, 16
	s_cbranch_scc1 .LBB0_440
	s_branch .Ldefer_conv_go

.Ldefer_conv_go:
	v_mov_b32_e32 v34, v225
	s_nop 0
	v_readfirstlane_b32 s2, v34
	s_ashr_i32 s19, s2, 6
	s_lshl_b32 s2, s70, 3
	s_add_i32 s3, s2, s19
	v_readlane_b32 s4, v255, 60
	s_cmp_eq_u32 s4, 0
	s_movk_i32 s4, 0xff00
	s_cbranch_scc1 .Ldefer_off_orig
	v_readlane_b32 s4, v255, 61
.Ldefer_off_orig:
	s_add_i32 s3, s3, s4
	s_cmpk_gt_i32 s3, 0x107f
	s_cbranch_scc1 .LBB0_440
	s_add_i32 s2, s18, 1
	s_add_i32 s34, s3, 0x380
	s_cmpk_gt_i32 s3, 0xfeff
	s_mov_b64 s[30:31], -1
	s_cbranch_scc0 .LBB0_420
	s_cmp_lt_u32 s3, 0xfffffc80
	s_cbranch_scc0 .LBB0_417
	s_mov_b64 s[28:29], -1
	s_cmpk_gt_u32 s34, 0xe7f
	s_mul_hi_i32 s13, s2, 0xb00000
	s_mul_i32 s17, s2, 0xb00000
	s_cbranch_scc0 .LBB0_415
	s_mov_b32 s6, 19
	s_ashr_i32 s7, s6, 31
	s_lshl_b64 s[6:7], s[6:7], 3
	s_add_u32 s6, s0, s6
	s_addc_u32 s7, s1, s7
	s_load_dwordx2 s[6:7], s[6:7], 0x0
	s_ashr_i32 s3, s2, 31
	s_mul_hi_i32 s4, s2, 0x580000
	s_waitcnt lgkmcnt(0)
	s_add_u32 s26, s6, s17
	s_addc_u32 s27, s7, s13
	s_lshl_b32 s6, s34, 1
	s_and_b32 s6, s6, 0x7fffffc0
	s_add_i32 s54, s6, 0xffffe300
	s_lshl_b64 s[6:7], s[54:55], 12
	s_add_u32 s6, s26, s6
	s_addc_u32 s7, s27, s7
	s_lshl_b32 s26, s34, 5
	s_and_b32 s28, s26, 0x3e0
	s_lshl_b32 s26, s28, 2
	s_add_u32 s26, s6, s26
	s_addc_u32 s27, s7, 0
	s_mul_i32 s6, s2, 0x580000
	s_add_u32 s6, s20, s6
	s_addc_u32 s4, s21, s4
	s_mulk_i32 s28, 0x1600
	s_add_u32 s28, s6, s28
	s_addc_u32 s4, s4, 0
	s_lshl_b64 s[6:7], s[54:55], 1
	s_add_u32 s6, s28, s6
	s_addc_u32 s4, s4, s7
	s_add_u32 s6, s6, 0x4200000
	s_addc_u32 s7, s4, 0
	s_mov_b64 s[28:29], 0

.LBB0_422:
	v_bfe_u32 v66, v34, 3, 3
	v_lshlrev_b32_e32 v0, 2, v34
	v_and_b32_e32 v36, 28, v0
	v_or_b32_e32 v68, 8, v66
	v_or_b32_e32 v70, 16, v66
	v_or_b32_e32 v72, 24, v66
	v_or_b32_e32 v67, 32, v66
	v_or_b32_e32 v69, 40, v66
	v_or_b32_e32 v71, 48, v66
	v_or_b32_e32 v73, 56, v66
	v_lshlrev_b32_e32 v0, 2, v36
	s_waitcnt vmcnt(0)
	v_mul_u32_u24_e32 v2, s28, v66
	v_mul_u32_u24_e32 v4, s28, v68
	s_waitcnt vmcnt(0)
	v_mul_u32_u24_e32 v10, s28, v70
	v_mul_u32_u24_e32 v12, s28, v72
	v_mul_u32_u24_e32 v18, s28, v67
	v_mul_u32_u24_e32 v20, s28, v69
	v_mul_u32_u24_e32 v28, s28, v71
	v_mul_u32_u24_e32 v30, s28, v73
	v_lshl_add_u64 v[26:27], s[26:27], 0, v[0:1]
	v_lshlrev_b32_e32 v2, 2, v2
	v_mov_b32_e32 v3, v1
	v_lshlrev_b32_e32 v4, 2, v4
	v_mov_b32_e32 v5, v1
	v_lshlrev_b32_e32 v10, 2, v10
	v_mov_b32_e32 v11, v1
	v_lshlrev_b32_e32 v12, 2, v12
	v_mov_b32_e32 v13, v1
	v_lshlrev_b32_e32 v18, 2, v18
	v_mov_b32_e32 v19, v1
	v_lshlrev_b32_e32 v20, 2, v20
	v_mov_b32_e32 v21, v1
	v_lshlrev_b32_e32 v28, 2, v28
	v_mov_b32_e32 v29, v1
	v_lshlrev_b32_e32 v30, 2, v30
	v_mov_b32_e32 v31, v1
	v_lshl_add_u64 v[2:3], v[26:27], 0, v[2:3]
	v_lshl_add_u64 v[6:7], v[26:27], 0, v[4:5]
	v_lshl_add_u64 v[10:11], v[26:27], 0, v[10:11]
	v_lshl_add_u64 v[14:15], v[26:27], 0, v[12:13]
	v_lshl_add_u64 v[18:19], v[26:27], 0, v[18:19]
	v_lshl_add_u64 v[22:23], v[26:27], 0, v[20:21]
	v_lshl_add_u64 v[28:29], v[26:27], 0, v[28:29]
	v_lshl_add_u64 v[30:31], v[26:27], 0, v[30:31]
	global_load_dwordx4 v[2:5], v[2:3], off
	s_nop 0
	global_load_dwordx4 v[6:9], v[6:7], off
	s_nop 0
	global_load_dwordx4 v[10:13], v[10:11], off
	s_nop 0
	global_load_dwordx4 v[14:17], v[14:15], off
	s_nop 0
	global_load_dwordx4 v[18:21], v[18:19], off
	s_nop 0
	global_load_dwordx4 v[22:25], v[22:23], off
	s_nop 0
	global_load_dwordx4 v[26:29], v[28:29], off
	s_nop 0
	global_load_dwordx4 v[30:33], v[30:31], off
	s_mulk_i32 s19, 0x3000
	s_add_i32 s30, s19, 0
	s_mul_i32 s4, s3, 0xb00000
	s_mul_hi_u32 s19, s2, 0xb00000
	s_add_i32 s19, s19, s4
	s_mul_i32 s4, s3, 0x580000
	s_mul_hi_u32 s26, s2, 0x580000
	s_add_i32 s17, s14, 0xffffff00
	v_readlane_b32 s49, v255, 60
	s_cmp_eq_u32 s49, 0
	s_cselect_b32 s17, s17, 0x300
	s_add_i32 s26, s26, s4
	s_mul_i32 s4, s2, 0x580000
	s_add_u32 s4, s20, s4
	s_addc_u32 s26, s21, s26
	s_add_u32 s39, s4, 0x4200000
	s_addc_u32 s40, s26, 0
	s_mul_i32 s4, s3, 0x1600000
	s_mul_hi_u32 s26, s2, 0x1600000
	s_mul_i32 s38, s2, 0xb00000
	s_add_i32 s41, s26, s4
	s_add_u32 s4, s36, s38
	s_addc_u32 s5, s5, s19
	s_lshl_b64 s[26:27], s[2:3], 20
	s_lshl_b64 s[28:29], s[2:3], 21
	s_add_u32 s28, s20, s28
	s_addc_u32 s29, s21, s29
	s_add_u32 s43, s28, 0xe00000
	s_addc_u32 s44, s29, 0
	s_mul_i32 s28, s3, 0x500000
	s_mul_hi_u32 s29, s2, 0x500000
	s_add_i32 s45, s29, s28
	s_mul_i32 s3, s3, 0x280000
	s_mul_hi_u32 s28, s2, 0x280000
	s_mul_i32 s42, s2, 0x1600000
	s_mul_i32 s46, s2, 0x500000
	s_add_i32 s28, s28, s3
	s_mul_i32 s2, s2, 0x280000
	s_add_u32 s2, s20, s2
	s_addc_u32 s3, s21, s28
	v_add_u32_e32 v35, s30, v0
	v_lshlrev_b32_e32 v0, 3, v34
	s_add_u32 s47, s2, 0x200000
	v_and_b32_e32 v34, 56, v0
	s_addc_u32 s48, s3, 0
	v_mul_u32_u24_e32 v37, 0x84, v66
	v_mul_u32_u24_e32 v0, 0x84, v34
	v_lshlrev_b32_e32 v38, 2, v66
	s_add_i32 s49, s34, s17
	v_add3_u32 v76, s30, v0, v38
	s_lshl_b32 s50, s49, 5
	s_lshl_b32 s51, s17, 5
	s_lshl_b32 s52, s49, 7
	s_lshl_b32 s53, s17, 7
	s_lshl_b32 s56, s49, 1
	s_lshl_b32 s57, s17, 1
	s_lshl_b64 s[26:27], s[26:27], 2
	v_lshlrev_b32_e32 v0, 2, v36
	v_add_u32_e32 v77, v35, v37
	v_lshlrev_b32_e32 v74, 1, v34
	s_mov_b64 s[2:3], s[6:7]
	s_mov_b32 s54, s13
	s_branch .LBB0_424

.LBB0_440:
	v_readlane_b32 s2, v255, 58
	s_cmp_eq_u32 s2, 1
	s_cbranch_scc0 .Ldefer_not
	v_readlane_b32 s2, v255, 61
	s_cmp_eq_u32 s2, 0xfffff900
	s_cbranch_scc0 .Ldefer_done
	s_cmp_gt_i32 s82, 16
	s_cbranch_scc1 .Ldefer_done
	s_mov_b32 s2, 0xfffffa00
	v_writelane_b32 v255, s2, 61
	s_add_u32 s36, s20, 0x1600000
	s_addc_u32 s5, s21, 0
	s_branch .Ldefer_conv_go
.Ldefer_done:
	s_waitcnt vmcnt(0) lgkmcnt(0)
	s_mov_b32 s2, 2
	v_writelane_b32 v255, s2, 58
	s_movk_i32 s2, 0x400
	v_writelane_b32 v255, s2, 59
	s_branch .LBB0_10

.LBB0_501:
	s_cmp_eq_u32 s2, 36
	s_cbranch_scc0 .Ldefer_nowait
	v_readlane_b32 s3, v255, 60
	s_cmp_eq_u32 s3, 0
	s_cbranch_scc1 .Ldefer_nowait
	v_readfirstlane_b32 s3, v225
	s_lshr_b32 s3, s3, 6
	s_cmp_eq_u32 s3, 0
	s_cbranch_scc0 .Ldefer_nowait
	s_load_dwordx2 s[76:77], s[0:1], 0xb0
	s_lshl_b32 s3, s18, 6
	s_add_i32 s3, s3, 0x3800
	s_waitcnt lgkmcnt(0)
	s_add_u32 s76, s76, s3
	s_addc_u32 s77, s77, 0
